# P1 norm+modulate: two rows per loop trip sharing the batch shift/scale loads (16 KB of x per wave in flight)
# speedup vs baseline: 1.0012x; 1.0012x over previous
; template <bool BF> __device__ __forceinline__ unsigned pk2(float lo, float hi) { return BF ? pk_bf2(lo, hi) : pk_h2(lo, hi); }
; template <bool BF, bool IN_F16> __device__ __forceinline__ void norm_mod_rows(const void* __restrict__ Xv, const float* __restrict__ gw, const float* __restrict__ mod, int sh_off, int sc_off,
;                                               h16* __restrict__ H, int G, int bid) {
;     ...
;     for (int r = bid * 8 + wave; r < NT; r += G * 8) {
;         const int b = r >> 13; f32x4 v[8]; float ss = 0.f;
;         if (IN_F16) { const h16* xr = (const h16*)Xv + (size_t)r * DM;
; #pragma unroll
;             for (int i = 0; i < 8; ++i) { const half4 hv = *(const half4*)(xr + 4 * (lane + 64 * i)); v[i] = (f32x4){(float)hv[0], (float)hv[1], (float)hv[2], (float)hv[3]}; } }
;         else { const float* xr = (const float*)Xv + (size_t)r * DM;
; #pragma unroll
;             for (int i = 0; i < 8; ++i) v[i] = *(const f32x4*)(xr + 4 * (lane + 64 * i)); }
; #pragma unroll
;         for (int i = 0; i < 8; ++i) ss += v[i][0] * v[i][0] + v[i][1] * v[i][1] + v[i][2] * v[i][2] + v[i][3] * v[i][3];
;         ss = wave_sum(ss); const float rstd = rsqrtf(ss * (1.f / DM) + EPS);
;         const float* mb = mod + (size_t)b * 12288;
; #pragma unroll
;         for (int i = 0; i < 8; ++i) { const int c = 4 * (lane + 64 * i);
;             const f32x4 g = *(const f32x4*)(gw + c), sh = *(const f32x4*)(mb + sh_off + c), sc = *(const f32x4*)(mb + sc_off + c);
;             const f32x4 o = (v[i] * rstd) * g * (1.f + sc) + sh;
;             u32x2 w; w.x = pg8::pk2<BF>(o[0], o[1]); w.y = pg8::pk2<BF>(o[2], o[3]);
;             *(u32x2*)(H + (size_t)r * DM + c) = w; }
;     }
.LBB0_192:
	global_load_dwordx4 v[54:57], v[72:73], off offset:-4096
	global_load_dwordx4 v[50:53], v[72:73], off offset:-3072
	global_load_dwordx4 v[42:45], v[72:73], off
	global_load_dwordx4 v[34:37], v[72:73], off offset:1024
	global_load_dwordx4 v[62:65], v[72:73], off offset:-2048
	global_load_dwordx4 v[58:61], v[72:73], off offset:-1024
	global_load_dwordx4 v[46:49], v[72:73], off offset:2048
	global_load_dwordx4 v[38:41], v[72:73], off offset:3072
	v_lshl_add_u64 v[206:207], v[72:73], 0, s[10:11]
	global_load_dwordx4 v[194:197], v[206:207], off offset:-4096
	global_load_dwordx4 v[190:193], v[206:207], off offset:-3072
	global_load_dwordx4 v[182:185], v[206:207], off
	global_load_dwordx4 v[174:177], v[206:207], off offset:1024
	global_load_dwordx4 v[202:205], v[206:207], off offset:-2048
	global_load_dwordx4 v[198:201], v[206:207], off offset:-1024
	global_load_dwordx4 v[186:189], v[206:207], off offset:2048
	global_load_dwordx4 v[178:181], v[206:207], off offset:3072
	v_ashrrev_i32_e32 v94, 13, v66
	v_mul_hi_i32_i24_e32 v95, 0xc000, v94
	v_mul_i32_i24_e32 v94, 0xc000, v94
	v_lshl_add_u64 v[94:95], s[68:69], 0, v[94:95]
	v_mov_b32_e32 v75, v69
	v_mov_b32_e32 v77, v69
	v_mov_b32_e32 v79, v69
	v_mov_b32_e32 v81, v69
	v_mov_b32_e32 v83, v69
	v_mov_b32_e32 v85, v69
	v_mov_b32_e32 v87, v69
	v_lshl_add_u64 v[118:119], v[94:95], 0, s[18:19]
	v_lshl_add_u64 v[110:111], v[94:95], 0, v[68:69]
	v_lshl_add_u64 v[112:113], v[94:95], 0, v[80:81]
	v_lshl_add_u64 v[114:115], v[94:95], 0, v[82:83]
	v_lshl_add_u64 v[150:151], v[94:95], 0, v[84:85]
	v_lshl_add_u64 v[154:155], v[94:95], 0, v[86:87]
	v_lshl_add_u64 v[120:121], v[118:119], 0, v[68:69]
	v_lshl_add_u64 v[122:123], v[118:119], 0, v[74:75]
	v_lshl_add_u64 v[126:127], v[118:119], 0, v[76:77]
	v_lshl_add_u64 v[130:131], v[118:119], 0, v[78:79]
	v_lshl_add_u64 v[134:135], v[118:119], 0, v[80:81]
	v_lshl_add_u64 v[138:139], v[118:119], 0, v[82:83]
	v_lshl_add_u64 v[142:143], v[118:119], 0, v[84:85]
	v_lshl_add_u64 v[146:147], v[118:119], 0, v[86:87]
	global_load_dwordx4 v[94:97], v[110:111], off
	global_load_dwordx4 v[98:101], v[110:111], off offset:1024
	global_load_dwordx4 v[102:105], v[110:111], off offset:2048
	global_load_dwordx4 v[106:109], v[110:111], off offset:3072
	v_add_u32_e32 v66, s6, v66
	v_add_u32_e32 v66, s6, v66
	global_load_dwordx4 v[110:113], v[112:113], off
	v_cmp_lt_i32_e32 vcc, s1, v66
	global_load_dwordx4 v[114:117], v[114:115], off
	s_nop 0
	global_load_dwordx4 v[118:121], v[120:121], off
	s_nop 0
	global_load_dwordx4 v[122:125], v[122:123], off
	s_nop 0
	global_load_dwordx4 v[126:129], v[126:127], off
	s_nop 0
	global_load_dwordx4 v[130:133], v[130:131], off
	s_nop 0
	global_load_dwordx4 v[134:137], v[134:135], off
	s_nop 0
	global_load_dwordx4 v[138:141], v[138:139], off
	s_nop 0
	global_load_dwordx4 v[142:145], v[142:143], off
	s_nop 0
	global_load_dwordx4 v[146:149], v[146:147], off
	s_nop 0
	global_load_dwordx4 v[150:153], v[150:151], off
	s_nop 0
	global_load_dwordx4 v[154:157], v[154:155], off
	s_or_b64 s[12:13], vcc, s[12:13]
	v_lshl_add_u64 v[72:73], v[72:73], 0, s[10:11]
	v_lshl_add_u64 v[72:73], v[72:73], 0, s[10:11]
	s_waitcnt vmcnt(31)
	v_mul_f32_e32 v75, v55, v55
	s_waitcnt vmcnt(30)
	v_mul_f32_e32 v77, v51, v51
	v_fmac_f32_e32 v75, v54, v54
	v_fmac_f32_e32 v77, v50, v50
	s_waitcnt vmcnt(27)
	v_mul_f32_e32 v79, v63, v63
	v_mov_b32_e32 v160, v43
	v_mov_b32_e32 v161, v35
	s_waitcnt vmcnt(26)
	v_mul_f32_e32 v81, v59, v59
	v_fmac_f32_e32 v79, v62, v62
	v_fmac_f32_e32 v75, v56, v56
	v_fmac_f32_e32 v77, v52, v52
	v_mov_b32_e32 v158, v42
	v_mov_b32_e32 v159, v34
	v_pk_mul_f32 v[160:161], v[160:161], v[160:161]
	v_fmac_f32_e32 v81, v58, v58
	v_fmac_f32_e32 v79, v64, v64
	v_fmac_f32_e32 v75, v57, v57
	v_fmac_f32_e32 v77, v53, v53
	s_waitcnt vmcnt(25)
	v_mov_b32_e32 v164, v47
	s_waitcnt vmcnt(24)
	v_mov_b32_e32 v165, v39
	v_mov_b32_e32 v166, v44
	v_mov_b32_e32 v167, v36
	v_pk_fma_f32 v[158:159], v[158:159], v[158:159], v[160:161]
	v_fmac_f32_e32 v81, v60, v60
	v_fmac_f32_e32 v79, v65, v65
	v_add_f32_e32 v75, v75, v77
	v_mov_b32_e32 v162, v46
	v_mov_b32_e32 v163, v38
	v_mov_b32_e32 v170, v45
	v_mov_b32_e32 v171, v37
	v_pk_mul_f32 v[164:165], v[164:165], v[164:165]
	v_pk_fma_f32 v[158:159], v[166:167], v[166:167], v[158:159]
	v_fmac_f32_e32 v81, v61, v61
	v_add_f32_e32 v75, v75, v79
	v_mov_b32_e32 v168, v48
	v_mov_b32_e32 v169, v40
	v_pk_fma_f32 v[160:161], v[162:163], v[162:163], v[164:165]
	v_pk_fma_f32 v[158:159], v[170:171], v[170:171], v[158:159]
	v_add_f32_e32 v75, v75, v81
	v_mov_b32_e32 v172, v49
	v_mov_b32_e32 v173, v41
	v_pk_fma_f32 v[160:161], v[168:169], v[168:169], v[160:161]
	v_add_f32_e32 v75, v75, v158
	v_pk_fma_f32 v[160:161], v[172:173], v[172:173], v[160:161]
	v_add_f32_e32 v75, v75, v159
	v_add_f32_e32 v75, v75, v160
	v_add_f32_e32 v75, v75, v161
	ds_bpermute_b32 v77, v88, v75
	s_waitcnt vmcnt(9)
	v_pk_add_f32 v[120:121], v[120:121], 1.0 op_sel_hi:[1,0]
	v_pk_add_f32 v[118:119], v[118:119], 1.0 op_sel_hi:[1,0]
	s_waitcnt vmcnt(8)
	v_pk_add_f32 v[124:125], v[124:125], 1.0 op_sel_hi:[1,0]
	v_pk_add_f32 v[122:123], v[122:123], 1.0 op_sel_hi:[1,0]
	s_waitcnt lgkmcnt(0)
	v_add_f32_e32 v75, v75, v77
	ds_bpermute_b32 v77, v89, v75
	s_waitcnt vmcnt(7)
	v_pk_add_f32 v[128:129], v[128:129], 1.0 op_sel_hi:[1,0]
	v_pk_add_f32 v[126:127], v[126:127], 1.0 op_sel_hi:[1,0]
	s_waitcnt vmcnt(6)
	v_pk_add_f32 v[132:133], v[132:133], 1.0 op_sel_hi:[1,0]
	v_pk_add_f32 v[130:131], v[130:131], 1.0 op_sel_hi:[1,0]
	s_waitcnt lgkmcnt(0)
	v_add_f32_e32 v75, v75, v77
	ds_bpermute_b32 v77, v90, v75
	s_waitcnt vmcnt(5)
; template <bool BF> __device__ __forceinline__ unsigned pk2(float lo, float hi) { return BF ? pk_bf2(lo, hi) : pk_h2(lo, hi); }
; template <bool BF, bool IN_F16> __device__ __forceinline__ void norm_mod_rows(const void* __restrict__ Xv, const float* __restrict__ gw, const float* __restrict__ mod, int sh_off, int sc_off,
;                                               h16* __restrict__ H, int G, int bid) {
;     ...
;         ss = wave_sum(ss); const float rstd = rsqrtf(ss * (1.f / DM) + EPS);
;         const float* mb = mod + (size_t)b * 12288;
; #pragma unroll
;         for (int i = 0; i < 8; ++i) { const int c = 4 * (lane + 64 * i);
;             const f32x4 g = *(const f32x4*)(gw + c), sh = *(const f32x4*)(mb + sh_off + c), sc = *(const f32x4*)(mb + sc_off + c);
;             const f32x4 o = (v[i] * rstd) * g * (1.f + sc) + sh;
;             u32x2 w; w.x = pg8::pk2<BF>(o[0], o[1]); w.y = pg8::pk2<BF>(o[2], o[3]);
;             *(u32x2*)(H + (size_t)r * DM + c) = w; }
	v_pk_add_f32 v[136:137], v[136:137], 1.0 op_sel_hi:[1,0]
	v_pk_add_f32 v[134:135], v[134:135], 1.0 op_sel_hi:[1,0]
	s_waitcnt vmcnt(4)
	v_pk_add_f32 v[140:141], v[140:141], 1.0 op_sel_hi:[1,0]
	v_pk_add_f32 v[138:139], v[138:139], 1.0 op_sel_hi:[1,0]
	s_waitcnt lgkmcnt(0)
	v_add_f32_e32 v75, v75, v77
	ds_bpermute_b32 v77, v91, v75
	s_waitcnt vmcnt(3)
	v_pk_add_f32 v[144:145], v[144:145], 1.0 op_sel_hi:[1,0]
	v_pk_add_f32 v[142:143], v[142:143], 1.0 op_sel_hi:[1,0]
	s_waitcnt vmcnt(2)
	v_pk_add_f32 v[148:149], v[148:149], 1.0 op_sel_hi:[1,0]
	v_pk_add_f32 v[146:147], v[146:147], 1.0 op_sel_hi:[1,0]
	s_waitcnt lgkmcnt(0)
	v_add_f32_e32 v75, v75, v77
	ds_bpermute_b32 v77, v92, v75
	s_waitcnt lgkmcnt(0)
	v_add_f32_e32 v75, v75, v77
	ds_bpermute_b32 v77, v93, v75
	s_waitcnt lgkmcnt(0)
	v_add_f32_e32 v75, v75, v77
	v_fmamk_f32 v75, v75, 0x3a000000, v67
	v_mul_f32_e32 v77, 0x4b800000, v75
	v_cmp_gt_f32_e32 vcc, s0, v75
	s_nop 1
	v_cndmask_b32_e32 v75, v75, v77, vcc
	v_rsq_f32_e32 v75, v75
	s_nop 0
	v_mul_f32_e32 v77, 0x45800000, v75
	v_cndmask_b32_e32 v158, v75, v77, vcc
	v_pk_mul_f32 v[56:57], v[56:57], v[158:159] op_sel_hi:[1,0]
	v_pk_mul_f32 v[54:55], v[54:55], v[158:159] op_sel_hi:[1,0]
	v_pk_mul_f32 v[52:53], v[52:53], v[158:159] op_sel_hi:[1,0]
	v_pk_mul_f32 v[50:51], v[50:51], v[158:159] op_sel_hi:[1,0]
	v_pk_mul_f32 v[64:65], v[64:65], v[158:159] op_sel_hi:[1,0]
	v_pk_mul_f32 v[62:63], v[62:63], v[158:159] op_sel_hi:[1,0]
	v_pk_mul_f32 v[60:61], v[60:61], v[158:159] op_sel_hi:[1,0]
	v_pk_mul_f32 v[58:59], v[58:59], v[158:159] op_sel_hi:[1,0]
	v_pk_mul_f32 v[44:45], v[44:45], v[158:159] op_sel_hi:[1,0]
	v_pk_mul_f32 v[42:43], v[42:43], v[158:159] op_sel_hi:[1,0]
	v_pk_mul_f32 v[36:37], v[36:37], v[158:159] op_sel_hi:[1,0]
	v_pk_mul_f32 v[34:35], v[34:35], v[158:159] op_sel_hi:[1,0]
	v_pk_mul_f32 v[48:49], v[48:49], v[158:159] op_sel_hi:[1,0]
	v_pk_mul_f32 v[46:47], v[46:47], v[158:159] op_sel_hi:[1,0]
	v_pk_mul_f32 v[40:41], v[40:41], v[158:159] op_sel_hi:[1,0]
	v_pk_mul_f32 v[38:39], v[38:39], v[158:159] op_sel_hi:[1,0]
	v_pk_mul_f32 v[54:55], v[2:3], v[54:55]
	v_pk_mul_f32 v[56:57], v[4:5], v[56:57]
	v_pk_mul_f32 v[52:53], v[8:9], v[52:53]
	v_pk_mul_f32 v[50:51], v[6:7], v[50:51]
	v_pk_mul_f32 v[64:65], v[12:13], v[64:65]
	v_pk_mul_f32 v[62:63], v[10:11], v[62:63]
	v_pk_mul_f32 v[60:61], v[16:17], v[60:61]
	v_pk_mul_f32 v[58:59], v[14:15], v[58:59]
	v_pk_mul_f32 v[44:45], v[20:21], v[44:45]
	v_pk_mul_f32 v[42:43], v[18:19], v[42:43]
	v_pk_mul_f32 v[34:35], v[22:23], v[34:35]
	v_pk_mul_f32 v[36:37], v[24:25], v[36:37]
	v_pk_mul_f32 v[46:47], v[26:27], v[46:47]
	v_pk_mul_f32 v[48:49], v[28:29], v[48:49]
	v_pk_mul_f32 v[38:39], v[30:31], v[38:39]
	v_pk_mul_f32 v[40:41], v[32:33], v[40:41]
	v_pk_fma_f32 v[56:57], v[120:121], v[56:57], v[96:97]
	v_pk_fma_f32 v[54:55], v[118:119], v[54:55], v[94:95]
	v_pk_fma_f32 v[52:53], v[124:125], v[52:53], v[100:101]
	v_pk_fma_f32 v[50:51], v[122:123], v[50:51], v[98:99]
	v_pk_fma_f32 v[64:65], v[128:129], v[64:65], v[104:105]
	v_pk_fma_f32 v[62:63], v[126:127], v[62:63], v[102:103]
	v_pk_fma_f32 v[60:61], v[132:133], v[60:61], v[108:109]
	v_pk_fma_f32 v[58:59], v[130:131], v[58:59], v[106:107]
	v_pk_fma_f32 v[44:45], v[136:137], v[44:45], v[112:113]
	v_pk_fma_f32 v[42:43], v[134:135], v[42:43], v[110:111]
	v_pk_fma_f32 v[36:37], v[36:37], v[140:141], v[116:117]
	v_pk_fma_f32 v[34:35], v[34:35], v[138:139], v[114:115]
	s_waitcnt vmcnt(1)
	v_pk_fma_f32 v[48:49], v[48:49], v[144:145], v[152:153]
	v_pk_fma_f32 v[46:47], v[46:47], v[142:143], v[150:151]
	s_waitcnt vmcnt(0)
	v_pk_fma_f32 v[40:41], v[40:41], v[148:149], v[156:157]
	v_pk_fma_f32 v[38:39], v[38:39], v[146:147], v[154:155]
	v_cvt_pk_f16_f32 v54, v54, v55
	v_cvt_pk_f16_f32 v55, v56, v57
	v_cvt_pk_f16_f32 v50, v50, v51
	v_cvt_pk_f16_f32 v51, v52, v53
	v_cvt_pk_f16_f32 v52, v62, v63
	v_cvt_pk_f16_f32 v53, v64, v65
	v_cvt_pk_f16_f32 v56, v58, v59
	v_cvt_pk_f16_f32 v57, v60, v61
	v_cvt_pk_f16_f32 v42, v42, v43
	v_cvt_pk_f16_f32 v43, v44, v45
	v_cvt_pk_f16_f32 v34, v34, v35
	v_cvt_pk_f16_f32 v35, v36, v37
	v_cvt_pk_f16_f32 v36, v46, v47
	v_cvt_pk_f16_f32 v37, v48, v49
	v_cvt_pk_f16_f32 v38, v38, v39
	v_cvt_pk_f16_f32 v39, v40, v41
	global_store_dwordx2 v[70:71], v[54:55], off
	global_store_dwordx2 v[70:71], v[50:51], off offset:512
	global_store_dwordx2 v[70:71], v[52:53], off offset:1024
	global_store_dwordx2 v[70:71], v[56:57], off offset:1536
	global_store_dwordx2 v[70:71], v[42:43], off offset:2048
	global_store_dwordx2 v[70:71], v[34:35], off offset:2560
	global_store_dwordx2 v[70:71], v[36:37], off offset:3072
	global_store_dwordx2 v[70:71], v[38:39], off offset:3584
	v_lshl_add_u64 v[70:71], v[70:71], 0, s[8:9]
	v_mul_f32_e32 v75, v195, v195
	v_mul_f32_e32 v77, v191, v191
	v_fmac_f32_e32 v75, v194, v194
	v_fmac_f32_e32 v77, v190, v190
	v_mul_f32_e32 v79, v203, v203
	v_mov_b32_e32 v160, v183
	v_mov_b32_e32 v161, v175
	v_mul_f32_e32 v81, v199, v199
	v_fmac_f32_e32 v79, v202, v202
	v_fmac_f32_e32 v75, v196, v196
	v_fmac_f32_e32 v77, v192, v192
	v_mov_b32_e32 v158, v182
	v_mov_b32_e32 v159, v174
	v_pk_mul_f32 v[160:161], v[160:161], v[160:161]
	v_fmac_f32_e32 v81, v198, v198
	v_fmac_f32_e32 v79, v204, v204
	v_fmac_f32_e32 v75, v197, v197
	v_fmac_f32_e32 v77, v193, v193
	v_mov_b32_e32 v164, v187
	v_mov_b32_e32 v165, v179
	v_mov_b32_e32 v166, v184
	v_mov_b32_e32 v167, v176
	v_pk_fma_f32 v[158:159], v[158:159], v[158:159], v[160:161]
	v_fmac_f32_e32 v81, v200, v200
	v_fmac_f32_e32 v79, v205, v205
	v_add_f32_e32 v75, v75, v77
	v_mov_b32_e32 v162, v186
	v_mov_b32_e32 v163, v178
	v_mov_b32_e32 v170, v185
	v_mov_b32_e32 v171, v177
	v_pk_mul_f32 v[164:165], v[164:165], v[164:165]
	v_pk_fma_f32 v[158:159], v[166:167], v[166:167], v[158:159]
	v_fmac_f32_e32 v81, v201, v201
	v_add_f32_e32 v75, v75, v79
	v_mov_b32_e32 v168, v188
	v_mov_b32_e32 v169, v180
	v_pk_fma_f32 v[160:161], v[162:163], v[162:163], v[164:165]
	v_pk_fma_f32 v[158:159], v[170:171], v[170:171], v[158:159]
	v_add_f32_e32 v75, v75, v81
	v_mov_b32_e32 v172, v189
	v_mov_b32_e32 v173, v181
	v_pk_fma_f32 v[160:161], v[168:169], v[168:169], v[160:161]
	v_add_f32_e32 v75, v75, v158
	v_pk_fma_f32 v[160:161], v[172:173], v[172:173], v[160:161]
	v_add_f32_e32 v75, v75, v159
	v_add_f32_e32 v75, v75, v160
	v_add_f32_e32 v75, v75, v161
	ds_bpermute_b32 v77, v88, v75
	s_waitcnt lgkmcnt(0)
; template <bool BF> __device__ __forceinline__ unsigned pk2(float lo, float hi) { return BF ? pk_bf2(lo, hi) : pk_h2(lo, hi); }
; template <bool BF, bool IN_F16> __device__ __forceinline__ void norm_mod_rows(const void* __restrict__ Xv, const float* __restrict__ gw, const float* __restrict__ mod, int sh_off, int sc_off,
;                                               h16* __restrict__ H, int G, int bid) {
;     ...
;         ss = wave_sum(ss); const float rstd = rsqrtf(ss * (1.f / DM) + EPS);
;         const float* mb = mod + (size_t)b * 12288;
; #pragma unroll
;         for (int i = 0; i < 8; ++i) { const int c = 4 * (lane + 64 * i);
;             const f32x4 g = *(const f32x4*)(gw + c), sh = *(const f32x4*)(mb + sh_off + c), sc = *(const f32x4*)(mb + sc_off + c);
;             const f32x4 o = (v[i] * rstd) * g * (1.f + sc) + sh;
;             u32x2 w; w.x = pg8::pk2<BF>(o[0], o[1]); w.y = pg8::pk2<BF>(o[2], o[3]);
;             *(u32x2*)(H + (size_t)r * DM + c) = w; }
	v_add_f32_e32 v75, v75, v77
	ds_bpermute_b32 v77, v89, v75
	s_waitcnt lgkmcnt(0)
	v_add_f32_e32 v75, v75, v77
	ds_bpermute_b32 v77, v90, v75
	s_waitcnt lgkmcnt(0)
	v_add_f32_e32 v75, v75, v77
	ds_bpermute_b32 v77, v91, v75
	s_waitcnt lgkmcnt(0)
	v_add_f32_e32 v75, v75, v77
	ds_bpermute_b32 v77, v92, v75
	s_waitcnt lgkmcnt(0)
	v_add_f32_e32 v75, v75, v77
	ds_bpermute_b32 v77, v93, v75
	s_waitcnt lgkmcnt(0)
	v_add_f32_e32 v75, v75, v77
	v_fmamk_f32 v75, v75, 0x3a000000, v67
	v_mul_f32_e32 v77, 0x4b800000, v75
	v_cmp_gt_f32_e32 vcc, s0, v75
	s_nop 1
	v_cndmask_b32_e32 v75, v75, v77, vcc
	v_rsq_f32_e32 v75, v75
	s_nop 0
	v_mul_f32_e32 v77, 0x45800000, v75
	v_cndmask_b32_e32 v158, v75, v77, vcc
	v_pk_mul_f32 v[196:197], v[196:197], v[158:159] op_sel_hi:[1,0]
	v_pk_mul_f32 v[194:195], v[194:195], v[158:159] op_sel_hi:[1,0]
	v_pk_mul_f32 v[192:193], v[192:193], v[158:159] op_sel_hi:[1,0]
	v_pk_mul_f32 v[190:191], v[190:191], v[158:159] op_sel_hi:[1,0]
	v_pk_mul_f32 v[204:205], v[204:205], v[158:159] op_sel_hi:[1,0]
	v_pk_mul_f32 v[202:203], v[202:203], v[158:159] op_sel_hi:[1,0]
	v_pk_mul_f32 v[200:201], v[200:201], v[158:159] op_sel_hi:[1,0]
	v_pk_mul_f32 v[198:199], v[198:199], v[158:159] op_sel_hi:[1,0]
	v_pk_mul_f32 v[184:185], v[184:185], v[158:159] op_sel_hi:[1,0]
	v_pk_mul_f32 v[182:183], v[182:183], v[158:159] op_sel_hi:[1,0]
	v_pk_mul_f32 v[176:177], v[176:177], v[158:159] op_sel_hi:[1,0]
	v_pk_mul_f32 v[174:175], v[174:175], v[158:159] op_sel_hi:[1,0]
	v_pk_mul_f32 v[188:189], v[188:189], v[158:159] op_sel_hi:[1,0]
	v_pk_mul_f32 v[186:187], v[186:187], v[158:159] op_sel_hi:[1,0]
	v_pk_mul_f32 v[180:181], v[180:181], v[158:159] op_sel_hi:[1,0]
	v_pk_mul_f32 v[178:179], v[178:179], v[158:159] op_sel_hi:[1,0]
	v_pk_mul_f32 v[194:195], v[2:3], v[194:195]
	v_pk_mul_f32 v[196:197], v[4:5], v[196:197]
	v_pk_mul_f32 v[192:193], v[8:9], v[192:193]
	v_pk_mul_f32 v[190:191], v[6:7], v[190:191]
	v_pk_mul_f32 v[204:205], v[12:13], v[204:205]
	v_pk_mul_f32 v[202:203], v[10:11], v[202:203]
	v_pk_mul_f32 v[200:201], v[16:17], v[200:201]
	v_pk_mul_f32 v[198:199], v[14:15], v[198:199]
	v_pk_mul_f32 v[184:185], v[20:21], v[184:185]
	v_pk_mul_f32 v[182:183], v[18:19], v[182:183]
	v_pk_mul_f32 v[174:175], v[22:23], v[174:175]
	v_pk_mul_f32 v[176:177], v[24:25], v[176:177]
	v_pk_mul_f32 v[186:187], v[26:27], v[186:187]
	v_pk_mul_f32 v[188:189], v[28:29], v[188:189]
	v_pk_mul_f32 v[178:179], v[30:31], v[178:179]
	v_pk_mul_f32 v[180:181], v[32:33], v[180:181]
	v_pk_fma_f32 v[196:197], v[120:121], v[196:197], v[96:97]
	v_pk_fma_f32 v[194:195], v[118:119], v[194:195], v[94:95]
	v_pk_fma_f32 v[192:193], v[124:125], v[192:193], v[100:101]
	v_pk_fma_f32 v[190:191], v[122:123], v[190:191], v[98:99]
	v_pk_fma_f32 v[204:205], v[128:129], v[204:205], v[104:105]
	v_pk_fma_f32 v[202:203], v[126:127], v[202:203], v[102:103]
	v_pk_fma_f32 v[200:201], v[132:133], v[200:201], v[108:109]
	v_pk_fma_f32 v[198:199], v[130:131], v[198:199], v[106:107]
	v_pk_fma_f32 v[184:185], v[136:137], v[184:185], v[112:113]
	v_pk_fma_f32 v[182:183], v[134:135], v[182:183], v[110:111]
	v_pk_fma_f32 v[176:177], v[176:177], v[140:141], v[116:117]
	v_pk_fma_f32 v[174:175], v[174:175], v[138:139], v[114:115]
	v_pk_fma_f32 v[188:189], v[188:189], v[144:145], v[152:153]
	v_pk_fma_f32 v[186:187], v[186:187], v[142:143], v[150:151]
	v_pk_fma_f32 v[180:181], v[180:181], v[148:149], v[156:157]
	v_pk_fma_f32 v[178:179], v[178:179], v[146:147], v[154:155]
	v_cvt_pk_f16_f32 v194, v194, v195
	v_cvt_pk_f16_f32 v195, v196, v197
	v_cvt_pk_f16_f32 v190, v190, v191
	v_cvt_pk_f16_f32 v191, v192, v193
	v_cvt_pk_f16_f32 v192, v202, v203
	v_cvt_pk_f16_f32 v193, v204, v205
	v_cvt_pk_f16_f32 v196, v198, v199
	v_cvt_pk_f16_f32 v197, v200, v201
	v_cvt_pk_f16_f32 v182, v182, v183
	v_cvt_pk_f16_f32 v183, v184, v185
	v_cvt_pk_f16_f32 v174, v174, v175
	v_cvt_pk_f16_f32 v175, v176, v177
	v_cvt_pk_f16_f32 v176, v186, v187
	v_cvt_pk_f16_f32 v177, v188, v189
	v_cvt_pk_f16_f32 v178, v178, v179
	v_cvt_pk_f16_f32 v179, v180, v181
	global_store_dwordx2 v[70:71], v[194:195], off
	global_store_dwordx2 v[70:71], v[190:191], off offset:512
	global_store_dwordx2 v[70:71], v[192:193], off offset:1024
	global_store_dwordx2 v[70:71], v[196:197], off offset:1536
	global_store_dwordx2 v[70:71], v[182:183], off offset:2048
	global_store_dwordx2 v[70:71], v[174:175], off offset:2560
	global_store_dwordx2 v[70:71], v[176:177], off offset:3072
	global_store_dwordx2 v[70:71], v[178:179], off offset:3584
	v_lshl_add_u64 v[70:71], v[70:71], 0, s[8:9]
	s_andn2_b64 exec, exec, s[12:13]
	s_cbranch_execnz .LBB0_192
